# rwkv chunk-state chain rewritten: 4-row-group lanes with dwordx4 P loads three chunks ahead, ds_swizzle broadcast, permlane reduce; v-residual LoRA stage-1 weight rows all in flight
# baseline (speedup 1.0000x reference)
; __device__ __forceinline__ int tidx() { int t = threadIdx.x; asm volatile("" : "+v"(t)); return t; }
; __device__ __forceinline__ int bidx() { int b = blockIdx.x; asm volatile("" : "+s"(b)); return b; }
; __device__ void phase_rwkv_chain(const Ctx& p, int l) {
;     ...
;     const int tid = tidx(); const int wave = __builtin_amdgcn_readfirstlane(tid >> 6), lane = tid & 63;
;     if (wave >= 4) return;
;     for (int it = bidx() * 4 + wave; it < 1024; it += gridDim.x * 4) {
;         const int b = it >> 9, h = (it >> 6) & 7, v = it & 63;
;         const float* pb = P + (size_t)((b * 64) * 8 + h) * 4096 + lane;
;         float* ub = UC + (size_t)((b * 64) * 8 + h) * 4096 + v * 64 + lane;
;         float row = 0.f; float PA[64], PB[64];
; #pragma unroll
;         for (int i = 0; i < 64; ++i) PA[i] = pb[i * 64];
;         float ucA = ub[0];
;         for (int c = 0; c < 64; c += 2) {
;             { const float* pc = pb + (size_t)(c + 1) * 32768;
; #pragma unroll
;               for (int i = 0; i < 64; ++i) PB[i] = pc[i * 64]; }
;             const float ucB = ub[(size_t)(c + 1) * 32768];
.LBB0_570:
	s_andn2_b64 vcc, exec, s[0:1]
	s_cbranch_vccnz .LBB0_581
	s_mov_b32 s0, s86
	s_mov_b32 s1, s87
	v_mov_b32_e32 v0, v184
	s_nop 0
	v_readfirstlane_b32 s2, v0
	s_ashr_i32 s6, s2, 6
	s_cmp_eq_u32 s6, 4
	s_cbranch_scc1 .Lsample_entry
	s_cmp_gt_i32 s6, 3
	s_cbranch_scc1 .LBB0_581
	s_mov_b32 s7, s90
	s_lshl_b32 s2, s7, 2
	s_add_i32 s2, s2, s6
	s_cmpk_gt_i32 s2, 0x3ff
	s_cbranch_scc1 .LBB0_581
	s_waitcnt lgkmcnt(0)
	s_and_b32 s3, s2, 0xfffffe00
	s_bfe_u32 s4, s2, 0x30006
	s_or_b32 s3, s3, s4
	s_lshl_b32 s3, s3, 14
	s_and_b32 s5, s2, 63
	s_lshl_b32 s5, s5, 8
	s_add_u32 s20, s0, 0x7700000
	s_addc_u32 s21, s1, 0
	s_add_u32 s20, s20, s3
	s_addc_u32 s21, s21, 0
	s_add_u32 s22, s0, 0x8700000
	s_addc_u32 s23, s1, 0
	s_add_u32 s22, s22, s3
	s_addc_u32 s23, s23, 0
	s_add_u32 s22, s22, s5
	s_addc_u32 s23, s23, 0
	s_mov_b64 s[24:25], s[22:23]
	s_and_b64 s[6:7], s[34:35], exec
	s_cselect_b32 s6, 2, 0
	s_lshr_b32 s7, s2, 9
	s_add_i32 s6, s6, s7
	s_lshl_b32 s6, s6, 17
	s_lshl_b32 s4, s4, 14
	s_add_i32 s6, s6, s4
	s_add_i32 s6, s6, s5
	s_add_u32 s6, s6, 0x4407200
	s_add_u32 s12, s84, s6
	s_addc_u32 s13, s85, 0
	v_and_b32_e32 v254, 63, v184
	v_lshlrev_b32_e32 v248, 4, v254
	v_add_u32_e32 v249, 0x1000, v248
	v_add_u32_e32 v250, 0x2000, v248
	v_add_u32_e32 v251, 0x3000, v248
	v_and_b32_e32 v255, 15, v254
	v_lshrrev_b32_e32 v254, 4, v254
	v_lshlrev_b32_e32 v255, 4, v255
	v_lshl_add_u32 v252, v254, 2, v255
	v_mov_b32_e32 v253, 0
	global_load_dwordx4 v[0:3], v248, s[20:21]
	global_load_dwordx4 v[4:7], v248, s[20:21] offset:1024
	global_load_dwordx4 v[8:11], v248, s[20:21] offset:2048
	global_load_dwordx4 v[12:15], v248, s[20:21] offset:3072
	global_load_dwordx4 v[16:19], v249, s[20:21]
	global_load_dwordx4 v[20:23], v249, s[20:21] offset:1024
	global_load_dwordx4 v[24:27], v249, s[20:21] offset:2048
	global_load_dwordx4 v[28:31], v249, s[20:21] offset:3072
	global_load_dwordx4 v[32:35], v250, s[20:21]
	global_load_dwordx4 v[36:39], v250, s[20:21] offset:1024
	global_load_dwordx4 v[40:43], v250, s[20:21] offset:2048
	global_load_dwordx4 v[44:47], v250, s[20:21] offset:3072
	global_load_dwordx4 v[48:51], v251, s[20:21]
	global_load_dwordx4 v[52:55], v251, s[20:21] offset:1024
	global_load_dwordx4 v[56:59], v251, s[20:21] offset:2048
	global_load_dwordx4 v[60:63], v251, s[20:21] offset:3072
	global_load_dword v236, v252, s[24:25]
	s_add_u32 s20, s20, 0x20000
	s_addc_u32 s21, s21, 0
	s_add_u32 s24, s24, 0x20000
	s_addc_u32 s25, s25, 0
	global_load_dwordx4 v[64:67], v248, s[20:21]
	global_load_dwordx4 v[68:71], v248, s[20:21] offset:1024
	global_load_dwordx4 v[72:75], v248, s[20:21] offset:2048
	global_load_dwordx4 v[76:79], v248, s[20:21] offset:3072
	global_load_dwordx4 v[80:83], v249, s[20:21]
	global_load_dwordx4 v[84:87], v249, s[20:21] offset:1024
	global_load_dwordx4 v[88:91], v249, s[20:21] offset:2048
	global_load_dwordx4 v[92:95], v249, s[20:21] offset:3072
	global_load_dwordx4 v[96:99], v250, s[20:21]
	global_load_dwordx4 v[100:103], v250, s[20:21] offset:1024
	global_load_dwordx4 v[104:107], v250, s[20:21] offset:2048
	global_load_dwordx4 v[108:111], v250, s[20:21] offset:3072
	global_load_dwordx4 v[112:115], v251, s[20:21]
	global_load_dwordx4 v[116:119], v251, s[20:21] offset:1024
	global_load_dwordx4 v[120:123], v251, s[20:21] offset:2048
	global_load_dwordx4 v[124:127], v251, s[20:21] offset:3072
	global_load_dword v237, v252, s[24:25]
	s_add_u32 s20, s20, 0x20000
	s_addc_u32 s21, s21, 0
	s_add_u32 s24, s24, 0x20000
	s_addc_u32 s25, s25, 0
	global_load_dwordx4 v[148:151], v248, s[20:21]
	global_load_dwordx4 v[152:155], v248, s[20:21] offset:1024
	global_load_dwordx4 v[156:159], v248, s[20:21] offset:2048
	global_load_dwordx4 v[160:163], v248, s[20:21] offset:3072
	global_load_dwordx4 v[164:167], v249, s[20:21]
	global_load_dwordx4 v[168:171], v249, s[20:21] offset:1024
	global_load_dwordx4 v[172:175], v249, s[20:21] offset:2048
	global_load_dwordx4 v[176:179], v249, s[20:21] offset:3072
	global_load_dwordx4 v[180:183], v250, s[20:21]
	global_load_dwordx4 v[192:195], v250, s[20:21] offset:1024
	global_load_dwordx4 v[196:199], v250, s[20:21] offset:2048
	global_load_dwordx4 v[200:203], v250, s[20:21] offset:3072
	global_load_dwordx4 v[204:207], v251, s[20:21]
	global_load_dwordx4 v[208:211], v251, s[20:21] offset:1024
	global_load_dwordx4 v[212:215], v251, s[20:21] offset:2048
	global_load_dwordx4 v[216:219], v251, s[20:21] offset:3072
	global_load_dword v238, v252, s[24:25]
	s_add_u32 s20, s20, 0x20000
	s_addc_u32 s21, s21, 0
	s_add_u32 s24, s24, 0x20000
	s_addc_u32 s25, s25, 0
	s_mov_b32 s26, 0
; __device__ __forceinline__ float rdl(float x, int i) { return __uint_as_float(__builtin_amdgcn_readlane(__float_as_uint(x), i)); }
; __device__ void phase_rwkv_chain(const Ctx& p, int l) {
;     ...
;         for (int c = 0; c < 64; c += 2) {
;             { const float* pc = pb + (size_t)(c + 1) * 32768;
; #pragma unroll
;               for (int i = 0; i < 64; ++i) PB[i] = pc[i * 64]; }
;             const float ucB = ub[(size_t)(c + 1) * 32768];
;             ub[(size_t)c * 32768] = row;
;             { float n0 = ucA, n1 = 0.f;
; #pragma unroll
;               for (int i = 0; i < 64; i += 2) { n0 = fmaf(rdl(row, i), PA[i], n0); n1 = fmaf(rdl(row, i + 1), PA[i + 1], n1); }
;               row = n0 + n1; }
;             if (c + 2 < 64) { const float* pc = pb + (size_t)(c + 2) * 32768;
; #pragma unroll
;                 for (int i = 0; i < 64; ++i) PA[i] = pc[i * 64];
;                 ucA = ub[(size_t)(c + 2) * 32768]; }
;             ub[(size_t)(c + 1) * 32768] = row;
;             { float n0 = ucB, n1 = 0.f;
; #pragma unroll
;               for (int i = 0; i < 64; i += 2) { n0 = fmaf(rdl(row, i), PB[i], n0); n1 = fmaf(rdl(row, i + 1), PB[i + 1], n1); }
;               row = n0 + n1; }
.Lrc_loop:
	global_store_dword v252, v253, s[22:23]
	ds_swizzle_b32 v220, v253 offset:0x10
	ds_swizzle_b32 v221, v253 offset:0x30
	ds_swizzle_b32 v222, v253 offset:0x50
	ds_swizzle_b32 v223, v253 offset:0x70
	ds_swizzle_b32 v224, v253 offset:0x90
	ds_swizzle_b32 v225, v253 offset:0xb0
	ds_swizzle_b32 v226, v253 offset:0xd0
	ds_swizzle_b32 v227, v253 offset:0xf0
	ds_swizzle_b32 v228, v253 offset:0x110
	ds_swizzle_b32 v229, v253 offset:0x130
	ds_swizzle_b32 v230, v253 offset:0x150
	ds_swizzle_b32 v231, v253 offset:0x170
	ds_swizzle_b32 v232, v253 offset:0x190
	ds_swizzle_b32 v233, v253 offset:0x1b0
	ds_swizzle_b32 v234, v253 offset:0x1d0
	s_waitcnt vmcnt(51) lgkmcnt(14)
	v_pk_mul_f32 v[244:245], v[220:221], v[0:1] op_sel_hi:[0,1]
	v_pk_mul_f32 v[246:247], v[220:221], v[2:3] op_sel_hi:[0,1]
	ds_swizzle_b32 v235, v253 offset:0x1f0
	global_load_dwordx4 v[0:3], v248, s[20:21]
	s_waitcnt vmcnt(51) lgkmcnt(14)
	v_pk_fma_f32 v[244:245], v[220:221], v[4:5], v[244:245] op_sel:[1,0,0] op_sel_hi:[1,1,1]
	v_pk_fma_f32 v[246:247], v[220:221], v[6:7], v[246:247] op_sel:[1,0,0] op_sel_hi:[1,1,1]
	global_load_dwordx4 v[4:7], v248, s[20:21] offset:1024
	s_waitcnt vmcnt(51) lgkmcnt(13)
	v_pk_fma_f32 v[244:245], v[222:223], v[8:9], v[244:245] op_sel_hi:[0,1,1]
	v_pk_fma_f32 v[246:247], v[222:223], v[10:11], v[246:247] op_sel_hi:[0,1,1]
	global_load_dwordx4 v[8:11], v248, s[20:21] offset:2048
	s_waitcnt vmcnt(51) lgkmcnt(12)
	v_pk_fma_f32 v[244:245], v[222:223], v[12:13], v[244:245] op_sel:[1,0,0] op_sel_hi:[1,1,1]
	v_pk_fma_f32 v[246:247], v[222:223], v[14:15], v[246:247] op_sel:[1,0,0] op_sel_hi:[1,1,1]
	global_load_dwordx4 v[12:15], v248, s[20:21] offset:3072
	s_waitcnt vmcnt(51) lgkmcnt(11)
	v_pk_fma_f32 v[244:245], v[224:225], v[16:17], v[244:245] op_sel_hi:[0,1,1]
	v_pk_fma_f32 v[246:247], v[224:225], v[18:19], v[246:247] op_sel_hi:[0,1,1]
	global_load_dwordx4 v[16:19], v249, s[20:21]
	s_waitcnt vmcnt(51) lgkmcnt(10)
	v_pk_fma_f32 v[244:245], v[224:225], v[20:21], v[244:245] op_sel:[1,0,0] op_sel_hi:[1,1,1]
	v_pk_fma_f32 v[246:247], v[224:225], v[22:23], v[246:247] op_sel:[1,0,0] op_sel_hi:[1,1,1]
	global_load_dwordx4 v[20:23], v249, s[20:21] offset:1024
	s_waitcnt vmcnt(51) lgkmcnt(9)
	v_pk_fma_f32 v[244:245], v[226:227], v[24:25], v[244:245] op_sel_hi:[0,1,1]
	v_pk_fma_f32 v[246:247], v[226:227], v[26:27], v[246:247] op_sel_hi:[0,1,1]
	global_load_dwordx4 v[24:27], v249, s[20:21] offset:2048
	s_waitcnt vmcnt(51) lgkmcnt(8)
	v_pk_fma_f32 v[244:245], v[226:227], v[28:29], v[244:245] op_sel:[1,0,0] op_sel_hi:[1,1,1]
	v_pk_fma_f32 v[246:247], v[226:227], v[30:31], v[246:247] op_sel:[1,0,0] op_sel_hi:[1,1,1]
	global_load_dwordx4 v[28:31], v249, s[20:21] offset:3072
	s_waitcnt vmcnt(51) lgkmcnt(7)
	v_pk_fma_f32 v[244:245], v[228:229], v[32:33], v[244:245] op_sel_hi:[0,1,1]
	v_pk_fma_f32 v[246:247], v[228:229], v[34:35], v[246:247] op_sel_hi:[0,1,1]
	global_load_dwordx4 v[32:35], v250, s[20:21]
	s_waitcnt vmcnt(51) lgkmcnt(6)
	v_pk_fma_f32 v[244:245], v[228:229], v[36:37], v[244:245] op_sel:[1,0,0] op_sel_hi:[1,1,1]
	v_pk_fma_f32 v[246:247], v[228:229], v[38:39], v[246:247] op_sel:[1,0,0] op_sel_hi:[1,1,1]
	global_load_dwordx4 v[36:39], v250, s[20:21] offset:1024
	s_waitcnt vmcnt(51) lgkmcnt(5)
	v_pk_fma_f32 v[244:245], v[230:231], v[40:41], v[244:245] op_sel_hi:[0,1,1]
	v_pk_fma_f32 v[246:247], v[230:231], v[42:43], v[246:247] op_sel_hi:[0,1,1]
	global_load_dwordx4 v[40:43], v250, s[20:21] offset:2048
	s_waitcnt vmcnt(51) lgkmcnt(4)
	v_pk_fma_f32 v[244:245], v[230:231], v[44:45], v[244:245] op_sel:[1,0,0] op_sel_hi:[1,1,1]
	v_pk_fma_f32 v[246:247], v[230:231], v[46:47], v[246:247] op_sel:[1,0,0] op_sel_hi:[1,1,1]
	global_load_dwordx4 v[44:47], v250, s[20:21] offset:3072
	s_waitcnt vmcnt(51) lgkmcnt(3)
	v_pk_fma_f32 v[244:245], v[232:233], v[48:49], v[244:245] op_sel_hi:[0,1,1]
	v_pk_fma_f32 v[246:247], v[232:233], v[50:51], v[246:247] op_sel_hi:[0,1,1]
	global_load_dwordx4 v[48:51], v251, s[20:21]
	s_waitcnt vmcnt(51) lgkmcnt(2)
	v_pk_fma_f32 v[244:245], v[232:233], v[52:53], v[244:245] op_sel:[1,0,0] op_sel_hi:[1,1,1]
	v_pk_fma_f32 v[246:247], v[232:233], v[54:55], v[246:247] op_sel:[1,0,0] op_sel_hi:[1,1,1]
	global_load_dwordx4 v[52:55], v251, s[20:21] offset:1024
	s_waitcnt vmcnt(51) lgkmcnt(1)
	v_pk_fma_f32 v[244:245], v[234:235], v[56:57], v[244:245] op_sel_hi:[0,1,1]
	v_pk_fma_f32 v[246:247], v[234:235], v[58:59], v[246:247] op_sel_hi:[0,1,1]
	global_load_dwordx4 v[56:59], v251, s[20:21] offset:2048
	s_waitcnt vmcnt(51) lgkmcnt(0)
	v_pk_fma_f32 v[244:245], v[234:235], v[60:61], v[244:245] op_sel:[1,0,0] op_sel_hi:[1,1,1]
	v_pk_fma_f32 v[246:247], v[234:235], v[62:63], v[246:247] op_sel:[1,0,0] op_sel_hi:[1,1,1]
	global_load_dwordx4 v[60:63], v251, s[20:21] offset:3072
	s_nop 1
	v_permlane16_swap_b32_e32 v244, v245
	s_nop 0
	v_permlane16_swap_b32_e32 v246, v247
	v_add_f32_e32 v244, v244, v245
	v_add_f32_e32 v246, v246, v247
	s_nop 1
	v_permlane32_swap_b32_e32 v244, v246
	s_waitcnt vmcnt(51)
	v_add_f32_e32 v244, v244, v246
	v_add_f32_e32 v253, v244, v236
	global_load_dword v236, v252, s[24:25]
	s_add_u32 s20, s20, 0x20000
	s_addc_u32 s21, s21, 0
	s_add_u32 s22, s22, 0x20000
	s_addc_u32 s23, s23, 0
	s_add_u32 s24, s24, 0x20000
	s_addc_u32 s25, s25, 0
	s_add_i32 s26, s26, 1
	s_cmp_eq_u32 s26, 64
	s_cbranch_scc1 .Lrc_done
; __device__ __forceinline__ float rdl(float x, int i) { return __uint_as_float(__builtin_amdgcn_readlane(__float_as_uint(x), i)); }
; __device__ void phase_rwkv_chain(const Ctx& p, int l) {
;     ...
;         for (int c = 0; c < 64; c += 2) {
;             { const float* pc = pb + (size_t)(c + 1) * 32768;
; #pragma unroll
;               for (int i = 0; i < 64; ++i) PB[i] = pc[i * 64]; }
;             const float ucB = ub[(size_t)(c + 1) * 32768];
;             ub[(size_t)c * 32768] = row;
;             { float n0 = ucA, n1 = 0.f;
; #pragma unroll
;               for (int i = 0; i < 64; i += 2) { n0 = fmaf(rdl(row, i), PA[i], n0); n1 = fmaf(rdl(row, i + 1), PA[i + 1], n1); }
;               row = n0 + n1; }
;             if (c + 2 < 64) { const float* pc = pb + (size_t)(c + 2) * 32768;
; #pragma unroll
;                 for (int i = 0; i < 64; ++i) PA[i] = pc[i * 64];
;                 ucA = ub[(size_t)(c + 2) * 32768]; }
;             ub[(size_t)(c + 1) * 32768] = row;
;             { float n0 = ucB, n1 = 0.f;
; #pragma unroll
;               for (int i = 0; i < 64; i += 2) { n0 = fmaf(rdl(row, i), PB[i], n0); n1 = fmaf(rdl(row, i + 1), PB[i + 1], n1); }
;               row = n0 + n1; }
	global_store_dword v252, v253, s[22:23]
	ds_swizzle_b32 v220, v253 offset:0x10
	ds_swizzle_b32 v221, v253 offset:0x30
	ds_swizzle_b32 v222, v253 offset:0x50
	ds_swizzle_b32 v223, v253 offset:0x70
	ds_swizzle_b32 v224, v253 offset:0x90
	ds_swizzle_b32 v225, v253 offset:0xb0
	ds_swizzle_b32 v226, v253 offset:0xd0
	ds_swizzle_b32 v227, v253 offset:0xf0
	ds_swizzle_b32 v228, v253 offset:0x110
	ds_swizzle_b32 v229, v253 offset:0x130
	ds_swizzle_b32 v230, v253 offset:0x150
	ds_swizzle_b32 v231, v253 offset:0x170
	ds_swizzle_b32 v232, v253 offset:0x190
	ds_swizzle_b32 v233, v253 offset:0x1b0
	ds_swizzle_b32 v234, v253 offset:0x1d0
	s_waitcnt vmcnt(51) lgkmcnt(14)
	v_pk_mul_f32 v[244:245], v[220:221], v[64:65] op_sel_hi:[0,1]
	v_pk_mul_f32 v[246:247], v[220:221], v[66:67] op_sel_hi:[0,1]
	ds_swizzle_b32 v235, v253 offset:0x1f0
	global_load_dwordx4 v[64:67], v248, s[20:21]
	s_waitcnt vmcnt(51) lgkmcnt(14)
	v_pk_fma_f32 v[244:245], v[220:221], v[68:69], v[244:245] op_sel:[1,0,0] op_sel_hi:[1,1,1]
	v_pk_fma_f32 v[246:247], v[220:221], v[70:71], v[246:247] op_sel:[1,0,0] op_sel_hi:[1,1,1]
	global_load_dwordx4 v[68:71], v248, s[20:21] offset:1024
	s_waitcnt vmcnt(51) lgkmcnt(13)
	v_pk_fma_f32 v[244:245], v[222:223], v[72:73], v[244:245] op_sel_hi:[0,1,1]
	v_pk_fma_f32 v[246:247], v[222:223], v[74:75], v[246:247] op_sel_hi:[0,1,1]
	global_load_dwordx4 v[72:75], v248, s[20:21] offset:2048
	s_waitcnt vmcnt(51) lgkmcnt(12)
	v_pk_fma_f32 v[244:245], v[222:223], v[76:77], v[244:245] op_sel:[1,0,0] op_sel_hi:[1,1,1]
	v_pk_fma_f32 v[246:247], v[222:223], v[78:79], v[246:247] op_sel:[1,0,0] op_sel_hi:[1,1,1]
	global_load_dwordx4 v[76:79], v248, s[20:21] offset:3072
	s_waitcnt vmcnt(51) lgkmcnt(11)
	v_pk_fma_f32 v[244:245], v[224:225], v[80:81], v[244:245] op_sel_hi:[0,1,1]
	v_pk_fma_f32 v[246:247], v[224:225], v[82:83], v[246:247] op_sel_hi:[0,1,1]
	global_load_dwordx4 v[80:83], v249, s[20:21]
	s_waitcnt vmcnt(51) lgkmcnt(10)
	v_pk_fma_f32 v[244:245], v[224:225], v[84:85], v[244:245] op_sel:[1,0,0] op_sel_hi:[1,1,1]
	v_pk_fma_f32 v[246:247], v[224:225], v[86:87], v[246:247] op_sel:[1,0,0] op_sel_hi:[1,1,1]
	global_load_dwordx4 v[84:87], v249, s[20:21] offset:1024
	s_waitcnt vmcnt(51) lgkmcnt(9)
	v_pk_fma_f32 v[244:245], v[226:227], v[88:89], v[244:245] op_sel_hi:[0,1,1]
	v_pk_fma_f32 v[246:247], v[226:227], v[90:91], v[246:247] op_sel_hi:[0,1,1]
	global_load_dwordx4 v[88:91], v249, s[20:21] offset:2048
	s_waitcnt vmcnt(51) lgkmcnt(8)
	v_pk_fma_f32 v[244:245], v[226:227], v[92:93], v[244:245] op_sel:[1,0,0] op_sel_hi:[1,1,1]
	v_pk_fma_f32 v[246:247], v[226:227], v[94:95], v[246:247] op_sel:[1,0,0] op_sel_hi:[1,1,1]
	global_load_dwordx4 v[92:95], v249, s[20:21] offset:3072
	s_waitcnt vmcnt(51) lgkmcnt(7)
	v_pk_fma_f32 v[244:245], v[228:229], v[96:97], v[244:245] op_sel_hi:[0,1,1]
	v_pk_fma_f32 v[246:247], v[228:229], v[98:99], v[246:247] op_sel_hi:[0,1,1]
	global_load_dwordx4 v[96:99], v250, s[20:21]
	s_waitcnt vmcnt(51) lgkmcnt(6)
	v_pk_fma_f32 v[244:245], v[228:229], v[100:101], v[244:245] op_sel:[1,0,0] op_sel_hi:[1,1,1]
	v_pk_fma_f32 v[246:247], v[228:229], v[102:103], v[246:247] op_sel:[1,0,0] op_sel_hi:[1,1,1]
	global_load_dwordx4 v[100:103], v250, s[20:21] offset:1024
	s_waitcnt vmcnt(51) lgkmcnt(5)
	v_pk_fma_f32 v[244:245], v[230:231], v[104:105], v[244:245] op_sel_hi:[0,1,1]
	v_pk_fma_f32 v[246:247], v[230:231], v[106:107], v[246:247] op_sel_hi:[0,1,1]
	global_load_dwordx4 v[104:107], v250, s[20:21] offset:2048
	s_waitcnt vmcnt(51) lgkmcnt(4)
	v_pk_fma_f32 v[244:245], v[230:231], v[108:109], v[244:245] op_sel:[1,0,0] op_sel_hi:[1,1,1]
	v_pk_fma_f32 v[246:247], v[230:231], v[110:111], v[246:247] op_sel:[1,0,0] op_sel_hi:[1,1,1]
	global_load_dwordx4 v[108:111], v250, s[20:21] offset:3072
	s_waitcnt vmcnt(51) lgkmcnt(3)
	v_pk_fma_f32 v[244:245], v[232:233], v[112:113], v[244:245] op_sel_hi:[0,1,1]
	v_pk_fma_f32 v[246:247], v[232:233], v[114:115], v[246:247] op_sel_hi:[0,1,1]
	global_load_dwordx4 v[112:115], v251, s[20:21]
	s_waitcnt vmcnt(51) lgkmcnt(2)
	v_pk_fma_f32 v[244:245], v[232:233], v[116:117], v[244:245] op_sel:[1,0,0] op_sel_hi:[1,1,1]
	v_pk_fma_f32 v[246:247], v[232:233], v[118:119], v[246:247] op_sel:[1,0,0] op_sel_hi:[1,1,1]
	global_load_dwordx4 v[116:119], v251, s[20:21] offset:1024
	s_waitcnt vmcnt(51) lgkmcnt(1)
	v_pk_fma_f32 v[244:245], v[234:235], v[120:121], v[244:245] op_sel_hi:[0,1,1]
	v_pk_fma_f32 v[246:247], v[234:235], v[122:123], v[246:247] op_sel_hi:[0,1,1]
	global_load_dwordx4 v[120:123], v251, s[20:21] offset:2048
	s_waitcnt vmcnt(51) lgkmcnt(0)
	v_pk_fma_f32 v[244:245], v[234:235], v[124:125], v[244:245] op_sel:[1,0,0] op_sel_hi:[1,1,1]
	v_pk_fma_f32 v[246:247], v[234:235], v[126:127], v[246:247] op_sel:[1,0,0] op_sel_hi:[1,1,1]
	global_load_dwordx4 v[124:127], v251, s[20:21] offset:3072
	s_nop 1
	v_permlane16_swap_b32_e32 v244, v245
	s_nop 0
	v_permlane16_swap_b32_e32 v246, v247
	v_add_f32_e32 v244, v244, v245
	v_add_f32_e32 v246, v246, v247
	s_nop 1
	v_permlane32_swap_b32_e32 v244, v246
	s_waitcnt vmcnt(51)
	v_add_f32_e32 v244, v244, v246
	v_add_f32_e32 v253, v244, v237
	global_load_dword v237, v252, s[24:25]
	s_add_u32 s20, s20, 0x20000
	s_addc_u32 s21, s21, 0
	s_add_u32 s22, s22, 0x20000
	s_addc_u32 s23, s23, 0
	s_add_u32 s24, s24, 0x20000
	s_addc_u32 s25, s25, 0
	s_add_i32 s26, s26, 1
	s_cmp_eq_u32 s26, 64
	s_cbranch_scc1 .Lrc_done
; __device__ __forceinline__ float rdl(float x, int i) { return __uint_as_float(__builtin_amdgcn_readlane(__float_as_uint(x), i)); }
; __device__ void phase_rwkv_chain(const Ctx& p, int l) {
;     ...
;         for (int c = 0; c < 64; c += 2) {
;             { const float* pc = pb + (size_t)(c + 1) * 32768;
; #pragma unroll
;               for (int i = 0; i < 64; ++i) PB[i] = pc[i * 64]; }
;             const float ucB = ub[(size_t)(c + 1) * 32768];
;             ub[(size_t)c * 32768] = row;
;             { float n0 = ucA, n1 = 0.f;
; #pragma unroll
;               for (int i = 0; i < 64; i += 2) { n0 = fmaf(rdl(row, i), PA[i], n0); n1 = fmaf(rdl(row, i + 1), PA[i + 1], n1); }
;               row = n0 + n1; }
;             if (c + 2 < 64) { const float* pc = pb + (size_t)(c + 2) * 32768;
; #pragma unroll
;                 for (int i = 0; i < 64; ++i) PA[i] = pc[i * 64];
;                 ucA = ub[(size_t)(c + 2) * 32768]; }
;             ub[(size_t)(c + 1) * 32768] = row;
;             { float n0 = ucB, n1 = 0.f;
; #pragma unroll
;               for (int i = 0; i < 64; i += 2) { n0 = fmaf(rdl(row, i), PB[i], n0); n1 = fmaf(rdl(row, i + 1), PB[i + 1], n1); }
;               row = n0 + n1; }
;         }
;         p.out[O_RWP + (((size_t)l * 2 + b) * 8 + h) * 4096 + v * 64 + lane] = row;
	global_store_dword v252, v253, s[22:23]
	ds_swizzle_b32 v220, v253 offset:0x10
	ds_swizzle_b32 v221, v253 offset:0x30
	ds_swizzle_b32 v222, v253 offset:0x50
	ds_swizzle_b32 v223, v253 offset:0x70
	ds_swizzle_b32 v224, v253 offset:0x90
	ds_swizzle_b32 v225, v253 offset:0xb0
	ds_swizzle_b32 v226, v253 offset:0xd0
	ds_swizzle_b32 v227, v253 offset:0xf0
	ds_swizzle_b32 v228, v253 offset:0x110
	ds_swizzle_b32 v229, v253 offset:0x130
	ds_swizzle_b32 v230, v253 offset:0x150
	ds_swizzle_b32 v231, v253 offset:0x170
	ds_swizzle_b32 v232, v253 offset:0x190
	ds_swizzle_b32 v233, v253 offset:0x1b0
	ds_swizzle_b32 v234, v253 offset:0x1d0
	s_waitcnt vmcnt(51) lgkmcnt(14)
	v_pk_mul_f32 v[244:245], v[220:221], v[148:149] op_sel_hi:[0,1]
	v_pk_mul_f32 v[246:247], v[220:221], v[150:151] op_sel_hi:[0,1]
	ds_swizzle_b32 v235, v253 offset:0x1f0
	global_load_dwordx4 v[148:151], v248, s[20:21]
	s_waitcnt vmcnt(51) lgkmcnt(14)
	v_pk_fma_f32 v[244:245], v[220:221], v[152:153], v[244:245] op_sel:[1,0,0] op_sel_hi:[1,1,1]
	v_pk_fma_f32 v[246:247], v[220:221], v[154:155], v[246:247] op_sel:[1,0,0] op_sel_hi:[1,1,1]
	global_load_dwordx4 v[152:155], v248, s[20:21] offset:1024
	s_waitcnt vmcnt(51) lgkmcnt(13)
	v_pk_fma_f32 v[244:245], v[222:223], v[156:157], v[244:245] op_sel_hi:[0,1,1]
	v_pk_fma_f32 v[246:247], v[222:223], v[158:159], v[246:247] op_sel_hi:[0,1,1]
	global_load_dwordx4 v[156:159], v248, s[20:21] offset:2048
	s_waitcnt vmcnt(51) lgkmcnt(12)
	v_pk_fma_f32 v[244:245], v[222:223], v[160:161], v[244:245] op_sel:[1,0,0] op_sel_hi:[1,1,1]
	v_pk_fma_f32 v[246:247], v[222:223], v[162:163], v[246:247] op_sel:[1,0,0] op_sel_hi:[1,1,1]
	global_load_dwordx4 v[160:163], v248, s[20:21] offset:3072
	s_waitcnt vmcnt(51) lgkmcnt(11)
	v_pk_fma_f32 v[244:245], v[224:225], v[164:165], v[244:245] op_sel_hi:[0,1,1]
	v_pk_fma_f32 v[246:247], v[224:225], v[166:167], v[246:247] op_sel_hi:[0,1,1]
	global_load_dwordx4 v[164:167], v249, s[20:21]
	s_waitcnt vmcnt(51) lgkmcnt(10)
	v_pk_fma_f32 v[244:245], v[224:225], v[168:169], v[244:245] op_sel:[1,0,0] op_sel_hi:[1,1,1]
	v_pk_fma_f32 v[246:247], v[224:225], v[170:171], v[246:247] op_sel:[1,0,0] op_sel_hi:[1,1,1]
	global_load_dwordx4 v[168:171], v249, s[20:21] offset:1024
	s_waitcnt vmcnt(51) lgkmcnt(9)
	v_pk_fma_f32 v[244:245], v[226:227], v[172:173], v[244:245] op_sel_hi:[0,1,1]
	v_pk_fma_f32 v[246:247], v[226:227], v[174:175], v[246:247] op_sel_hi:[0,1,1]
	global_load_dwordx4 v[172:175], v249, s[20:21] offset:2048
	s_waitcnt vmcnt(51) lgkmcnt(8)
	v_pk_fma_f32 v[244:245], v[226:227], v[176:177], v[244:245] op_sel:[1,0,0] op_sel_hi:[1,1,1]
	v_pk_fma_f32 v[246:247], v[226:227], v[178:179], v[246:247] op_sel:[1,0,0] op_sel_hi:[1,1,1]
	global_load_dwordx4 v[176:179], v249, s[20:21] offset:3072
	s_waitcnt vmcnt(51) lgkmcnt(7)
	v_pk_fma_f32 v[244:245], v[228:229], v[180:181], v[244:245] op_sel_hi:[0,1,1]
	v_pk_fma_f32 v[246:247], v[228:229], v[182:183], v[246:247] op_sel_hi:[0,1,1]
	global_load_dwordx4 v[180:183], v250, s[20:21]
	s_waitcnt vmcnt(51) lgkmcnt(6)
	v_pk_fma_f32 v[244:245], v[228:229], v[192:193], v[244:245] op_sel:[1,0,0] op_sel_hi:[1,1,1]
	v_pk_fma_f32 v[246:247], v[228:229], v[194:195], v[246:247] op_sel:[1,0,0] op_sel_hi:[1,1,1]
	global_load_dwordx4 v[192:195], v250, s[20:21] offset:1024
	s_waitcnt vmcnt(51) lgkmcnt(5)
	v_pk_fma_f32 v[244:245], v[230:231], v[196:197], v[244:245] op_sel_hi:[0,1,1]
	v_pk_fma_f32 v[246:247], v[230:231], v[198:199], v[246:247] op_sel_hi:[0,1,1]
	global_load_dwordx4 v[196:199], v250, s[20:21] offset:2048
	s_waitcnt vmcnt(51) lgkmcnt(4)
	v_pk_fma_f32 v[244:245], v[230:231], v[200:201], v[244:245] op_sel:[1,0,0] op_sel_hi:[1,1,1]
	v_pk_fma_f32 v[246:247], v[230:231], v[202:203], v[246:247] op_sel:[1,0,0] op_sel_hi:[1,1,1]
	global_load_dwordx4 v[200:203], v250, s[20:21] offset:3072
	s_waitcnt vmcnt(51) lgkmcnt(3)
	v_pk_fma_f32 v[244:245], v[232:233], v[204:205], v[244:245] op_sel_hi:[0,1,1]
	v_pk_fma_f32 v[246:247], v[232:233], v[206:207], v[246:247] op_sel_hi:[0,1,1]
	global_load_dwordx4 v[204:207], v251, s[20:21]
	s_waitcnt vmcnt(51) lgkmcnt(2)
	v_pk_fma_f32 v[244:245], v[232:233], v[208:209], v[244:245] op_sel:[1,0,0] op_sel_hi:[1,1,1]
	v_pk_fma_f32 v[246:247], v[232:233], v[210:211], v[246:247] op_sel:[1,0,0] op_sel_hi:[1,1,1]
	global_load_dwordx4 v[208:211], v251, s[20:21] offset:1024
	s_waitcnt vmcnt(51) lgkmcnt(1)
	v_pk_fma_f32 v[244:245], v[234:235], v[212:213], v[244:245] op_sel_hi:[0,1,1]
	v_pk_fma_f32 v[246:247], v[234:235], v[214:215], v[246:247] op_sel_hi:[0,1,1]
	global_load_dwordx4 v[212:215], v251, s[20:21] offset:2048
	s_waitcnt vmcnt(51) lgkmcnt(0)
	v_pk_fma_f32 v[244:245], v[234:235], v[216:217], v[244:245] op_sel:[1,0,0] op_sel_hi:[1,1,1]
	v_pk_fma_f32 v[246:247], v[234:235], v[218:219], v[246:247] op_sel:[1,0,0] op_sel_hi:[1,1,1]
	global_load_dwordx4 v[216:219], v251, s[20:21] offset:3072
	s_nop 1
	v_permlane16_swap_b32_e32 v244, v245
	s_nop 0
	v_permlane16_swap_b32_e32 v246, v247
	v_add_f32_e32 v244, v244, v245
	v_add_f32_e32 v246, v246, v247
	s_nop 1
	v_permlane32_swap_b32_e32 v244, v246
	s_waitcnt vmcnt(51)
	v_add_f32_e32 v244, v244, v246
	v_add_f32_e32 v253, v244, v238
	global_load_dword v238, v252, s[24:25]
	s_add_u32 s20, s20, 0x20000
	s_addc_u32 s21, s21, 0
	s_add_u32 s22, s22, 0x20000
	s_addc_u32 s23, s23, 0
	s_add_u32 s24, s24, 0x20000
	s_addc_u32 s25, s25, 0
	s_add_i32 s26, s26, 1
	s_cmp_lg_u32 s26, 64
	s_cbranch_scc1 .Lrc_loop
.Lrc_done:
	s_waitcnt vmcnt(0)
	global_store_dword v252, v253, s[12:13]

; __device__ __forceinline__ u32x2 pack4(float a, float b, float c, float d) { u32x2 w; w.x = cvt_pk_bf16(a, b); w.y = cvt_pk_bf16(c, d); return w; }
; __device__ void phase_prep(const Ctx& p, int l, LAS unsigned char* lds) {
;     ...
;             if (wave < 4) {
;                 const int tt = wave & 1, ot = wave >> 1; f32x4 acc = (f32x4){0.f, 0.f, 0.f, 0.f};
; #pragma unroll 4
;                 for (int ks = 0; ks < 16; ++ks) {
;                     const bf16x8 X = *(const bf16x8*)(v1T + (ot * 16 + fr) * 512 + ks * 32 + fq * 8);
;                     const bf16x8 Y = *(const LAS bf16x8*)(MX + (tt * 16 + fr) * MXS + 1024 + ks * 32 + fq * 8);
;                     acc = __builtin_amdgcn_mfma_f32_16x16x32_bf16(X, Y, acc, 0, 0, 0); }
;                 *(LAS u32x2*)(MID + (tt * 16 + fr) * MIDS + ot * 16 + 4 * fq) = pack4(acc[0], acc[1], acc[2], acc[3]);
;             }
.LBB0_1141:
	v_add_co_u32_e32 v14, vcc, 0x2048000, v106
	s_nop 1
	v_addc_co_u32_e32 v15, vcc, 0, v107, vcc
	global_load_dwordx4 v[196:199], v[14:15], off
	global_load_dwordx4 v[200:203], v[14:15], off offset:64
	global_load_dwordx4 v[204:207], v[14:15], off offset:128
	global_load_dwordx4 v[208:211], v[14:15], off offset:192
	global_load_dwordx4 v[212:215], v[14:15], off offset:256
	global_load_dwordx4 v[216:219], v[14:15], off offset:320
	global_load_dwordx4 v[220:223], v[14:15], off offset:384
	global_load_dwordx4 v[224:227], v[14:15], off offset:448
	global_load_dwordx4 v[228:231], v[14:15], off offset:512
	global_load_dwordx4 v[232:235], v[14:15], off offset:576
	global_load_dwordx4 v[236:239], v[14:15], off offset:640
	global_load_dwordx4 v[244:247], v[14:15], off offset:704
	global_load_dwordx4 v[248:251], v[14:15], off offset:768
	global_load_dwordx4 v[252:255], v[14:15], off offset:832
	global_load_dwordx4 v[6:9], v[14:15], off offset:896
	global_load_dwordx4 v[10:13], v[14:15], off offset:960
	ds_read_b128 v[108:111], v4
	ds_read_b128 v[112:115], v4 offset:64
	ds_read_b128 v[116:119], v4 offset:128
	s_waitcnt vmcnt(15) lgkmcnt(2)
	v_mfma_f32_16x16x32_bf16 v[0:3], v[196:199], v[108:111], v[0:3]
	ds_read_b128 v[108:111], v4 offset:192
	s_waitcnt vmcnt(14) lgkmcnt(2)
	v_mfma_f32_16x16x32_bf16 v[0:3], v[200:203], v[112:115], v[0:3]
	ds_read_b128 v[112:115], v4 offset:256
	s_waitcnt vmcnt(13) lgkmcnt(2)
	v_mfma_f32_16x16x32_bf16 v[0:3], v[204:207], v[116:119], v[0:3]
	ds_read_b128 v[116:119], v4 offset:320
	s_waitcnt vmcnt(12) lgkmcnt(2)
	v_mfma_f32_16x16x32_bf16 v[0:3], v[208:211], v[108:111], v[0:3]
	ds_read_b128 v[108:111], v4 offset:384
	s_waitcnt vmcnt(11) lgkmcnt(2)
	v_mfma_f32_16x16x32_bf16 v[0:3], v[212:215], v[112:115], v[0:3]
	ds_read_b128 v[112:115], v4 offset:448
	s_waitcnt vmcnt(10) lgkmcnt(2)
	v_mfma_f32_16x16x32_bf16 v[0:3], v[216:219], v[116:119], v[0:3]
	ds_read_b128 v[116:119], v4 offset:512
	s_waitcnt vmcnt(9) lgkmcnt(2)
	v_mfma_f32_16x16x32_bf16 v[0:3], v[220:223], v[108:111], v[0:3]
	ds_read_b128 v[108:111], v4 offset:576
	s_waitcnt vmcnt(8) lgkmcnt(2)
	v_mfma_f32_16x16x32_bf16 v[0:3], v[224:227], v[112:115], v[0:3]
	ds_read_b128 v[112:115], v4 offset:640
	s_waitcnt vmcnt(7) lgkmcnt(2)
	v_mfma_f32_16x16x32_bf16 v[0:3], v[228:231], v[116:119], v[0:3]
	ds_read_b128 v[116:119], v4 offset:704
	s_waitcnt vmcnt(6) lgkmcnt(2)
	v_mfma_f32_16x16x32_bf16 v[0:3], v[232:235], v[108:111], v[0:3]
	ds_read_b128 v[108:111], v4 offset:768
	s_waitcnt vmcnt(5) lgkmcnt(2)
	v_mfma_f32_16x16x32_bf16 v[0:3], v[236:239], v[112:115], v[0:3]
	ds_read_b128 v[112:115], v4 offset:832
	s_waitcnt vmcnt(4) lgkmcnt(2)
	v_mfma_f32_16x16x32_bf16 v[0:3], v[244:247], v[116:119], v[0:3]
	ds_read_b128 v[116:119], v4 offset:896
	s_waitcnt vmcnt(3) lgkmcnt(2)
	v_mfma_f32_16x16x32_bf16 v[0:3], v[248:251], v[108:111], v[0:3]
	ds_read_b128 v[108:111], v4 offset:960
	s_waitcnt vmcnt(2) lgkmcnt(2)
	v_mfma_f32_16x16x32_bf16 v[0:3], v[252:255], v[112:115], v[0:3]
	s_waitcnt vmcnt(1) lgkmcnt(1)
	v_mfma_f32_16x16x32_bf16 v[0:3], v[6:9], v[116:119], v[0:3]
	s_waitcnt vmcnt(0) lgkmcnt(0)
	v_mfma_f32_16x16x32_bf16 v[0:3], v[10:13], v[108:111], v[0:3]
	s_mov_b64 s[58:59], 0x400
	s_nop 4
	s_nop 6
	v_cvt_pk_bf16_f32 v0, v0, v1
	v_cvt_pk_bf16_f32 v1, v2, v3
	ds_write_b64 v175, v[0:1]
